# loop-edge edit: nine GEMM K-loop heads aligned to 64-byte instruction-cache lines
# speedup vs baseline: 1.0039x; 1.0021x over previous
; template <class Units>
; DI void gemm_phase(LAS unsigned char* lds, const int wid, const int lda, const int ldb, const int K, const Units& U) {
;     ...
;     for (int ui = 0;; ++ui) {
;         const bool has_next = U.get(ui + 1, pa, pb, Enxt);
;         const char* nA = has_next ? (const char*)pa : cA; const char* nB = has_next ? (const char*)pb : cB;
;         for (int t = 0; t < nt; t += 2) {
.LBB0_174:
	v_mov_b32_e32 v0, 0
	s_mov_b32 s19, -2
	s_mov_b32 s52, 0x60080
	v_mov_b32_e32 v1, v0
	v_mov_b32_e32 v2, v0
	v_mov_b32_e32 v3, v0
	v_mov_b32_e32 v4, v0
	v_mov_b32_e32 v5, v0
	v_mov_b32_e32 v6, v0
	v_mov_b32_e32 v7, v0
	v_mov_b32_e32 v8, v0
	v_mov_b32_e32 v9, v0
	v_mov_b32_e32 v10, v0
	v_mov_b32_e32 v11, v0
	v_mov_b32_e32 v12, v0
	v_mov_b32_e32 v13, v0
	v_mov_b32_e32 v14, v0
	v_mov_b32_e32 v15, v0
	v_mov_b32_e32 v24, v0
	v_mov_b32_e32 v25, v0
	v_mov_b32_e32 v26, v0
	v_mov_b32_e32 v27, v0
	v_mov_b32_e32 v28, v0
	v_mov_b32_e32 v29, v0
	v_mov_b32_e32 v30, v0
	v_mov_b32_e32 v31, v0
	v_mov_b32_e32 v40, v0
	v_mov_b32_e32 v41, v0
	v_mov_b32_e32 v42, v0
	v_mov_b32_e32 v43, v0
	v_mov_b32_e32 v44, v0
	v_mov_b32_e32 v45, v0
	v_mov_b32_e32 v46, v0
	v_mov_b32_e32 v47, v0
	v_mov_b32_e32 v16, v0
	v_mov_b32_e32 v17, v0
	v_mov_b32_e32 v18, v0
	v_mov_b32_e32 v19, v0
	v_mov_b32_e32 v20, v0
	v_mov_b32_e32 v21, v0
	v_mov_b32_e32 v22, v0
	v_mov_b32_e32 v23, v0
	v_mov_b32_e32 v32, v0
	v_mov_b32_e32 v33, v0
	v_mov_b32_e32 v34, v0
	v_mov_b32_e32 v35, v0
	v_mov_b32_e32 v36, v0
	v_mov_b32_e32 v37, v0
	v_mov_b32_e32 v38, v0
	v_mov_b32_e32 v39, v0
	v_mov_b32_e32 v48, v0
	v_mov_b32_e32 v49, v0
	v_mov_b32_e32 v50, v0
	v_mov_b32_e32 v51, v0
	v_mov_b32_e32 v52, v0
	v_mov_b32_e32 v53, v0
	v_mov_b32_e32 v54, v0
	v_mov_b32_e32 v55, v0
	v_mov_b32_e32 v56, v0
	v_mov_b32_e32 v57, v0
	v_mov_b32_e32 v58, v0
	v_mov_b32_e32 v59, v0
	v_mov_b32_e32 v60, v0
	v_mov_b32_e32 v61, v0
	v_mov_b32_e32 v62, v0
	v_mov_b32_e32 v63, v0
	v_mov_b32_e32 v64, v0
	v_mov_b32_e32 v65, v0
	v_mov_b32_e32 v66, v0
	v_mov_b32_e32 v67, v0
	v_mov_b32_e32 v68, v0
	v_mov_b32_e32 v69, v0
	v_mov_b32_e32 v70, v0
	v_mov_b32_e32 v71, v0
	v_mov_b32_e32 v72, v0
	v_mov_b32_e32 v73, v0
	v_mov_b32_e32 v74, v0
	v_mov_b32_e32 v75, v0
	v_mov_b32_e32 v76, v0
	v_mov_b32_e32 v77, v0
	v_mov_b32_e32 v78, v0
	v_mov_b32_e32 v79, v0
	v_mov_b32_e32 v88, v0
	v_mov_b32_e32 v89, v0
	v_mov_b32_e32 v90, v0
	v_mov_b32_e32 v91, v0
	v_mov_b32_e32 v92, v0
	v_mov_b32_e32 v93, v0
	v_mov_b32_e32 v94, v0
	v_mov_b32_e32 v95, v0
	v_mov_b32_e32 v104, v0
	v_mov_b32_e32 v105, v0
	v_mov_b32_e32 v106, v0
	v_mov_b32_e32 v107, v0
	v_mov_b32_e32 v108, v0
	v_mov_b32_e32 v109, v0
	v_mov_b32_e32 v110, v0
	v_mov_b32_e32 v111, v0
	v_mov_b32_e32 v80, v0
	v_mov_b32_e32 v81, v0
	v_mov_b32_e32 v82, v0
	v_mov_b32_e32 v83, v0
	v_mov_b32_e32 v84, v0
	v_mov_b32_e32 v85, v0
	v_mov_b32_e32 v86, v0
	v_mov_b32_e32 v87, v0
	v_mov_b32_e32 v96, v0
	v_mov_b32_e32 v97, v0
	v_mov_b32_e32 v98, v0
	v_mov_b32_e32 v99, v0
	v_mov_b32_e32 v100, v0
	v_mov_b32_e32 v101, v0
	v_mov_b32_e32 v102, v0
	v_mov_b32_e32 v103, v0
	v_mov_b32_e32 v112, v0
	v_mov_b32_e32 v113, v0
	v_mov_b32_e32 v114, v0
	v_mov_b32_e32 v115, v0
	v_mov_b32_e32 v116, v0
	v_mov_b32_e32 v117, v0
	v_mov_b32_e32 v118, v0
	v_mov_b32_e32 v119, v0
	v_mov_b32_e32 v120, v0
	v_mov_b32_e32 v121, v0
	v_mov_b32_e32 v122, v0
	v_mov_b32_e32 v123, v0
	v_mov_b32_e32 v124, v0
	v_mov_b32_e32 v125, v0
	v_mov_b32_e32 v126, v0
	v_mov_b32_e32 v127, v0
	.p2align	6

; template <class Units>
; DI void gemm_phase(LAS unsigned char* lds, const int wid, const int lda, const int ldb, const int K, const Units& U) {
;     ...
;     for (int ui = 0;; ++ui) {
;         const bool has_next = U.get(ui + 1, pa, pb, Enxt);
;         const char* nA = has_next ? (const char*)pa : cA; const char* nB = has_next ? (const char*)pb : cB;
;         for (int t = 0; t < nt; t += 2) {
.LBB0_861:
	v_mov_b32_e32 v0, 0
	s_mov_b32 s43, -2
	s_mov_b32 s44, 0x30080
	v_mov_b32_e32 v1, v0
	v_mov_b32_e32 v2, v0
	v_mov_b32_e32 v3, v0
	v_mov_b32_e32 v4, v0
	v_mov_b32_e32 v5, v0
	v_mov_b32_e32 v6, v0
	v_mov_b32_e32 v7, v0
	v_mov_b32_e32 v16, v0
	v_mov_b32_e32 v17, v0
	v_mov_b32_e32 v18, v0
	v_mov_b32_e32 v19, v0
	v_mov_b32_e32 v20, v0
	v_mov_b32_e32 v21, v0
	v_mov_b32_e32 v22, v0
	v_mov_b32_e32 v23, v0
	v_mov_b32_e32 v32, v0
	v_mov_b32_e32 v33, v0
	v_mov_b32_e32 v34, v0
	v_mov_b32_e32 v35, v0
	v_mov_b32_e32 v36, v0
	v_mov_b32_e32 v37, v0
	v_mov_b32_e32 v38, v0
	v_mov_b32_e32 v39, v0
	v_mov_b32_e32 v48, v0
	v_mov_b32_e32 v49, v0
	v_mov_b32_e32 v50, v0
	v_mov_b32_e32 v51, v0
	v_mov_b32_e32 v52, v0
	v_mov_b32_e32 v53, v0
	v_mov_b32_e32 v54, v0
	v_mov_b32_e32 v55, v0
	v_mov_b32_e32 v8, v0
	v_mov_b32_e32 v9, v0
	v_mov_b32_e32 v10, v0
	v_mov_b32_e32 v11, v0
	v_mov_b32_e32 v12, v0
	v_mov_b32_e32 v13, v0
	v_mov_b32_e32 v14, v0
	v_mov_b32_e32 v15, v0
	v_mov_b32_e32 v24, v0
	v_mov_b32_e32 v25, v0
	v_mov_b32_e32 v26, v0
	v_mov_b32_e32 v27, v0
	v_mov_b32_e32 v28, v0
	v_mov_b32_e32 v29, v0
	v_mov_b32_e32 v30, v0
	v_mov_b32_e32 v31, v0
	v_mov_b32_e32 v40, v0
	v_mov_b32_e32 v41, v0
	v_mov_b32_e32 v42, v0
	v_mov_b32_e32 v43, v0
	v_mov_b32_e32 v44, v0
	v_mov_b32_e32 v45, v0
	v_mov_b32_e32 v46, v0
	v_mov_b32_e32 v47, v0
	v_mov_b32_e32 v56, v0
	v_mov_b32_e32 v57, v0
	v_mov_b32_e32 v58, v0
	v_mov_b32_e32 v59, v0
	v_mov_b32_e32 v60, v0
	v_mov_b32_e32 v61, v0
	v_mov_b32_e32 v62, v0
	v_mov_b32_e32 v63, v0
	v_mov_b32_e32 v64, v0
	v_mov_b32_e32 v65, v0
	v_mov_b32_e32 v66, v0
	v_mov_b32_e32 v67, v0
	v_mov_b32_e32 v68, v0
	v_mov_b32_e32 v69, v0
	v_mov_b32_e32 v70, v0
	v_mov_b32_e32 v71, v0
	v_mov_b32_e32 v80, v0
	v_mov_b32_e32 v81, v0
	v_mov_b32_e32 v82, v0
	v_mov_b32_e32 v83, v0
	v_mov_b32_e32 v84, v0
	v_mov_b32_e32 v85, v0
	v_mov_b32_e32 v86, v0
	v_mov_b32_e32 v87, v0
	v_mov_b32_e32 v96, v0
	v_mov_b32_e32 v97, v0
	v_mov_b32_e32 v98, v0
	v_mov_b32_e32 v99, v0
	v_mov_b32_e32 v100, v0
	v_mov_b32_e32 v101, v0
	v_mov_b32_e32 v102, v0
	v_mov_b32_e32 v103, v0
	v_mov_b32_e32 v112, v0
	v_mov_b32_e32 v113, v0
	v_mov_b32_e32 v114, v0
	v_mov_b32_e32 v115, v0
	v_mov_b32_e32 v116, v0
	v_mov_b32_e32 v117, v0
	v_mov_b32_e32 v118, v0
	v_mov_b32_e32 v119, v0
	v_mov_b32_e32 v72, v0
	v_mov_b32_e32 v73, v0
	v_mov_b32_e32 v74, v0
	v_mov_b32_e32 v75, v0
	v_mov_b32_e32 v76, v0
	v_mov_b32_e32 v77, v0
	v_mov_b32_e32 v78, v0
	v_mov_b32_e32 v79, v0
	v_mov_b32_e32 v88, v0
	v_mov_b32_e32 v89, v0
	v_mov_b32_e32 v90, v0
	v_mov_b32_e32 v91, v0
	v_mov_b32_e32 v92, v0
	v_mov_b32_e32 v93, v0
	v_mov_b32_e32 v94, v0
	v_mov_b32_e32 v95, v0
	v_mov_b32_e32 v104, v0
	v_mov_b32_e32 v105, v0
	v_mov_b32_e32 v106, v0
	v_mov_b32_e32 v107, v0
	v_mov_b32_e32 v108, v0
	v_mov_b32_e32 v109, v0
	v_mov_b32_e32 v110, v0
	v_mov_b32_e32 v111, v0
	v_mov_b32_e32 v120, v0
	v_mov_b32_e32 v121, v0
	v_mov_b32_e32 v122, v0
	v_mov_b32_e32 v123, v0
	v_mov_b32_e32 v124, v0
	v_mov_b32_e32 v125, v0
	v_mov_b32_e32 v126, v0
	v_mov_b32_e32 v127, v0
	.p2align	6

; template <class Units>
; DI void gemm_phase(LAS unsigned char* lds, const int wid, const int lda, const int ldb, const int K, const Units& U) {
;     ...
;     for (int ui = 0;; ++ui) {
;         const bool has_next = U.get(ui + 1, pa, pb, Enxt);
;         const char* nA = has_next ? (const char*)pa : cA; const char* nB = has_next ? (const char*)pb : cB;
;         for (int t = 0; t < nt; t += 2) {
.LBB0_932:
	v_mov_b32_e32 v0, 0
	s_mov_b32 s23, -2
	s_mov_b32 s43, 0x60080
	v_mov_b32_e32 v1, v0
	v_mov_b32_e32 v2, v0
	v_mov_b32_e32 v3, v0
	v_mov_b32_e32 v4, v0
	v_mov_b32_e32 v5, v0
	v_mov_b32_e32 v6, v0
	v_mov_b32_e32 v7, v0
	v_mov_b32_e32 v8, v0
	v_mov_b32_e32 v9, v0
	v_mov_b32_e32 v10, v0
	v_mov_b32_e32 v11, v0
	v_mov_b32_e32 v12, v0
	v_mov_b32_e32 v13, v0
	v_mov_b32_e32 v14, v0
	v_mov_b32_e32 v15, v0
	v_mov_b32_e32 v24, v0
	v_mov_b32_e32 v25, v0
	v_mov_b32_e32 v26, v0
	v_mov_b32_e32 v27, v0
	v_mov_b32_e32 v28, v0
	v_mov_b32_e32 v29, v0
	v_mov_b32_e32 v30, v0
	v_mov_b32_e32 v31, v0
	v_mov_b32_e32 v40, v0
	v_mov_b32_e32 v41, v0
	v_mov_b32_e32 v42, v0
	v_mov_b32_e32 v43, v0
	v_mov_b32_e32 v44, v0
	v_mov_b32_e32 v45, v0
	v_mov_b32_e32 v46, v0
	v_mov_b32_e32 v47, v0
	v_mov_b32_e32 v16, v0
	v_mov_b32_e32 v17, v0
	v_mov_b32_e32 v18, v0
	v_mov_b32_e32 v19, v0
	v_mov_b32_e32 v20, v0
	v_mov_b32_e32 v21, v0
	v_mov_b32_e32 v22, v0
	v_mov_b32_e32 v23, v0
	v_mov_b32_e32 v32, v0
	v_mov_b32_e32 v33, v0
	v_mov_b32_e32 v34, v0
	v_mov_b32_e32 v35, v0
	v_mov_b32_e32 v36, v0
	v_mov_b32_e32 v37, v0
	v_mov_b32_e32 v38, v0
	v_mov_b32_e32 v39, v0
	v_mov_b32_e32 v48, v0
	v_mov_b32_e32 v49, v0
	v_mov_b32_e32 v50, v0
	v_mov_b32_e32 v51, v0
	v_mov_b32_e32 v52, v0
	v_mov_b32_e32 v53, v0
	v_mov_b32_e32 v54, v0
	v_mov_b32_e32 v55, v0
	v_mov_b32_e32 v56, v0
	v_mov_b32_e32 v57, v0
	v_mov_b32_e32 v58, v0
	v_mov_b32_e32 v59, v0
	v_mov_b32_e32 v60, v0
	v_mov_b32_e32 v61, v0
	v_mov_b32_e32 v62, v0
	v_mov_b32_e32 v63, v0
	v_mov_b32_e32 v64, v0
	v_mov_b32_e32 v65, v0
	v_mov_b32_e32 v66, v0
	v_mov_b32_e32 v67, v0
	v_mov_b32_e32 v68, v0
	v_mov_b32_e32 v69, v0
	v_mov_b32_e32 v70, v0
	v_mov_b32_e32 v71, v0
	v_mov_b32_e32 v72, v0
	v_mov_b32_e32 v73, v0
	v_mov_b32_e32 v74, v0
	v_mov_b32_e32 v75, v0
	v_mov_b32_e32 v76, v0
	v_mov_b32_e32 v77, v0
	v_mov_b32_e32 v78, v0
	v_mov_b32_e32 v79, v0
	v_mov_b32_e32 v88, v0
	v_mov_b32_e32 v89, v0
	v_mov_b32_e32 v90, v0
	v_mov_b32_e32 v91, v0
	v_mov_b32_e32 v92, v0
	v_mov_b32_e32 v93, v0
	v_mov_b32_e32 v94, v0
	v_mov_b32_e32 v95, v0
	v_mov_b32_e32 v104, v0
	v_mov_b32_e32 v105, v0
	v_mov_b32_e32 v106, v0
	v_mov_b32_e32 v107, v0
	v_mov_b32_e32 v108, v0
	v_mov_b32_e32 v109, v0
	v_mov_b32_e32 v110, v0
	v_mov_b32_e32 v111, v0
	v_mov_b32_e32 v80, v0
	v_mov_b32_e32 v81, v0
	v_mov_b32_e32 v82, v0
	v_mov_b32_e32 v83, v0
	v_mov_b32_e32 v84, v0
	v_mov_b32_e32 v85, v0
	v_mov_b32_e32 v86, v0
	v_mov_b32_e32 v87, v0
	v_mov_b32_e32 v96, v0
	v_mov_b32_e32 v97, v0
	v_mov_b32_e32 v98, v0
	v_mov_b32_e32 v99, v0
	v_mov_b32_e32 v100, v0
	v_mov_b32_e32 v101, v0
	v_mov_b32_e32 v102, v0
	v_mov_b32_e32 v103, v0
	v_mov_b32_e32 v112, v0
	v_mov_b32_e32 v113, v0
	v_mov_b32_e32 v114, v0
	v_mov_b32_e32 v115, v0
	v_mov_b32_e32 v116, v0
	v_mov_b32_e32 v117, v0
	v_mov_b32_e32 v118, v0
	v_mov_b32_e32 v119, v0
	v_mov_b32_e32 v120, v0
	v_mov_b32_e32 v121, v0
	v_mov_b32_e32 v122, v0
	v_mov_b32_e32 v123, v0
	v_mov_b32_e32 v124, v0
	v_mov_b32_e32 v125, v0
	v_mov_b32_e32 v126, v0
	v_mov_b32_e32 v127, v0
	.p2align	6

; template <class Units>
; DI void gemm_phase(LAS unsigned char* lds, const int wid, const int lda, const int ldb, const int K, const Units& U) {
;     ...
;     for (int ui = 0;; ++ui) {
;         const bool has_next = U.get(ui + 1, pa, pb, Enxt);
;         const char* nA = has_next ? (const char*)pa : cA; const char* nB = has_next ? (const char*)pb : cB;
;         for (int t = 0; t < nt; t += 2) {
.LBB0_1053:
	v_mov_b32_e32 v0, 0
	s_mov_b32 s44, -2
	s_mov_b32 s45, 0x60080
	v_mov_b32_e32 v1, v0
	v_mov_b32_e32 v2, v0
	v_mov_b32_e32 v3, v0
	v_mov_b32_e32 v8, v0
	v_mov_b32_e32 v9, v0
	v_mov_b32_e32 v10, v0
	v_mov_b32_e32 v11, v0
	v_mov_b32_e32 v16, v0
	v_mov_b32_e32 v17, v0
	v_mov_b32_e32 v18, v0
	v_mov_b32_e32 v19, v0
	v_mov_b32_e32 v24, v0
	v_mov_b32_e32 v25, v0
	v_mov_b32_e32 v26, v0
	v_mov_b32_e32 v27, v0
	v_mov_b32_e32 v32, v0
	v_mov_b32_e32 v33, v0
	v_mov_b32_e32 v34, v0
	v_mov_b32_e32 v35, v0
	v_mov_b32_e32 v40, v0
	v_mov_b32_e32 v41, v0
	v_mov_b32_e32 v42, v0
	v_mov_b32_e32 v43, v0
	v_mov_b32_e32 v48, v0
	v_mov_b32_e32 v49, v0
	v_mov_b32_e32 v50, v0
	v_mov_b32_e32 v51, v0
	v_mov_b32_e32 v56, v0
	v_mov_b32_e32 v57, v0
	v_mov_b32_e32 v58, v0
	v_mov_b32_e32 v59, v0
	v_mov_b32_e32 v4, v0
	v_mov_b32_e32 v5, v0
	v_mov_b32_e32 v6, v0
	v_mov_b32_e32 v7, v0
	v_mov_b32_e32 v12, v0
	v_mov_b32_e32 v13, v0
	v_mov_b32_e32 v14, v0
	v_mov_b32_e32 v15, v0
	v_mov_b32_e32 v20, v0
	v_mov_b32_e32 v21, v0
	v_mov_b32_e32 v22, v0
	v_mov_b32_e32 v23, v0
	v_mov_b32_e32 v28, v0
	v_mov_b32_e32 v29, v0
	v_mov_b32_e32 v30, v0
	v_mov_b32_e32 v31, v0
	v_mov_b32_e32 v36, v0
	v_mov_b32_e32 v37, v0
	v_mov_b32_e32 v38, v0
	v_mov_b32_e32 v39, v0
	v_mov_b32_e32 v44, v0
	v_mov_b32_e32 v45, v0
	v_mov_b32_e32 v46, v0
	v_mov_b32_e32 v47, v0
	v_mov_b32_e32 v52, v0
	v_mov_b32_e32 v53, v0
	v_mov_b32_e32 v54, v0
	v_mov_b32_e32 v55, v0
	v_mov_b32_e32 v60, v0
	v_mov_b32_e32 v61, v0
	v_mov_b32_e32 v62, v0
	v_mov_b32_e32 v63, v0
	v_mov_b32_e32 v64, v0
	v_mov_b32_e32 v65, v0
	v_mov_b32_e32 v66, v0
	v_mov_b32_e32 v67, v0
	v_mov_b32_e32 v72, v0
	v_mov_b32_e32 v73, v0
	v_mov_b32_e32 v74, v0
	v_mov_b32_e32 v75, v0
	v_mov_b32_e32 v80, v0
	v_mov_b32_e32 v81, v0
	v_mov_b32_e32 v82, v0
	v_mov_b32_e32 v83, v0
	v_mov_b32_e32 v88, v0
	v_mov_b32_e32 v89, v0
	v_mov_b32_e32 v90, v0
	v_mov_b32_e32 v91, v0
	v_mov_b32_e32 v96, v0
	v_mov_b32_e32 v97, v0
	v_mov_b32_e32 v98, v0
	v_mov_b32_e32 v99, v0
	v_mov_b32_e32 v104, v0
	v_mov_b32_e32 v105, v0
	v_mov_b32_e32 v106, v0
	v_mov_b32_e32 v107, v0
	v_mov_b32_e32 v112, v0
	v_mov_b32_e32 v113, v0
	v_mov_b32_e32 v114, v0
	v_mov_b32_e32 v115, v0
	v_mov_b32_e32 v120, v0
	v_mov_b32_e32 v121, v0
	v_mov_b32_e32 v122, v0
	v_mov_b32_e32 v123, v0
	v_mov_b32_e32 v68, v0
	v_mov_b32_e32 v69, v0
	v_mov_b32_e32 v70, v0
	v_mov_b32_e32 v71, v0
	v_mov_b32_e32 v76, v0
	v_mov_b32_e32 v77, v0
	v_mov_b32_e32 v78, v0
	v_mov_b32_e32 v79, v0
	v_mov_b32_e32 v84, v0
	v_mov_b32_e32 v85, v0
	v_mov_b32_e32 v86, v0
	v_mov_b32_e32 v87, v0
	v_mov_b32_e32 v92, v0
	v_mov_b32_e32 v93, v0
	v_mov_b32_e32 v94, v0
	v_mov_b32_e32 v95, v0
	v_mov_b32_e32 v100, v0
	v_mov_b32_e32 v101, v0
	v_mov_b32_e32 v102, v0
	v_mov_b32_e32 v103, v0
	v_mov_b32_e32 v108, v0
	v_mov_b32_e32 v109, v0
	v_mov_b32_e32 v110, v0
	v_mov_b32_e32 v111, v0
	v_mov_b32_e32 v116, v0
	v_mov_b32_e32 v117, v0
	v_mov_b32_e32 v118, v0
	v_mov_b32_e32 v119, v0
	v_mov_b32_e32 v124, v0
	v_mov_b32_e32 v125, v0
	v_mov_b32_e32 v126, v0
	v_mov_b32_e32 v127, v0
	.p2align	6

; template <class Units>
; DI void gemm_phase(LAS unsigned char* lds, const int wid, const int lda, const int ldb, const int K, const Units& U) {
;     ...
;     for (int ui = 0;; ++ui) {
;         const bool has_next = U.get(ui + 1, pa, pb, Enxt);
;         const char* nA = has_next ? (const char*)pa : cA; const char* nB = has_next ? (const char*)pb : cB;
;         for (int t = 0; t < nt; t += 2) {
.LBB0_1124:
	v_mov_b32_e32 v0, 0
	s_mov_b32 s23, -2
	s_mov_b32 s43, 0x108080
	v_mov_b32_e32 v1, v0
	v_mov_b32_e32 v2, v0
	v_mov_b32_e32 v3, v0
	v_mov_b32_e32 v4, v0
	v_mov_b32_e32 v5, v0
	v_mov_b32_e32 v6, v0
	v_mov_b32_e32 v7, v0
	v_mov_b32_e32 v8, v0
	v_mov_b32_e32 v9, v0
	v_mov_b32_e32 v10, v0
	v_mov_b32_e32 v11, v0
	v_mov_b32_e32 v12, v0
	v_mov_b32_e32 v13, v0
	v_mov_b32_e32 v14, v0
	v_mov_b32_e32 v15, v0
	v_mov_b32_e32 v24, v0
	v_mov_b32_e32 v25, v0
	v_mov_b32_e32 v26, v0
	v_mov_b32_e32 v27, v0
	v_mov_b32_e32 v28, v0
	v_mov_b32_e32 v29, v0
	v_mov_b32_e32 v30, v0
	v_mov_b32_e32 v31, v0
	v_mov_b32_e32 v40, v0
	v_mov_b32_e32 v41, v0
	v_mov_b32_e32 v42, v0
	v_mov_b32_e32 v43, v0
	v_mov_b32_e32 v44, v0
	v_mov_b32_e32 v45, v0
	v_mov_b32_e32 v46, v0
	v_mov_b32_e32 v47, v0
	v_mov_b32_e32 v16, v0
	v_mov_b32_e32 v17, v0
	v_mov_b32_e32 v18, v0
	v_mov_b32_e32 v19, v0
	v_mov_b32_e32 v20, v0
	v_mov_b32_e32 v21, v0
	v_mov_b32_e32 v22, v0
	v_mov_b32_e32 v23, v0
	v_mov_b32_e32 v32, v0
	v_mov_b32_e32 v33, v0
	v_mov_b32_e32 v34, v0
	v_mov_b32_e32 v35, v0
	v_mov_b32_e32 v36, v0
	v_mov_b32_e32 v37, v0
	v_mov_b32_e32 v38, v0
	v_mov_b32_e32 v39, v0
	v_mov_b32_e32 v48, v0
	v_mov_b32_e32 v49, v0
	v_mov_b32_e32 v50, v0
	v_mov_b32_e32 v51, v0
	v_mov_b32_e32 v52, v0
	v_mov_b32_e32 v53, v0
	v_mov_b32_e32 v54, v0
	v_mov_b32_e32 v55, v0
	v_mov_b32_e32 v56, v0
	v_mov_b32_e32 v57, v0
	v_mov_b32_e32 v58, v0
	v_mov_b32_e32 v59, v0
	v_mov_b32_e32 v60, v0
	v_mov_b32_e32 v61, v0
	v_mov_b32_e32 v62, v0
	v_mov_b32_e32 v63, v0
	v_mov_b32_e32 v64, v0
	v_mov_b32_e32 v65, v0
	v_mov_b32_e32 v66, v0
	v_mov_b32_e32 v67, v0
	v_mov_b32_e32 v68, v0
	v_mov_b32_e32 v69, v0
	v_mov_b32_e32 v70, v0
	v_mov_b32_e32 v71, v0
	v_mov_b32_e32 v72, v0
	v_mov_b32_e32 v73, v0
	v_mov_b32_e32 v74, v0
	v_mov_b32_e32 v75, v0
	v_mov_b32_e32 v76, v0
	v_mov_b32_e32 v77, v0
	v_mov_b32_e32 v78, v0
	v_mov_b32_e32 v79, v0
	v_mov_b32_e32 v88, v0
	v_mov_b32_e32 v89, v0
	v_mov_b32_e32 v90, v0
	v_mov_b32_e32 v91, v0
	v_mov_b32_e32 v92, v0
	v_mov_b32_e32 v93, v0
	v_mov_b32_e32 v94, v0
	v_mov_b32_e32 v95, v0
	v_mov_b32_e32 v104, v0
	v_mov_b32_e32 v105, v0
	v_mov_b32_e32 v106, v0
	v_mov_b32_e32 v107, v0
	v_mov_b32_e32 v108, v0
	v_mov_b32_e32 v109, v0
	v_mov_b32_e32 v110, v0
	v_mov_b32_e32 v111, v0
	v_mov_b32_e32 v80, v0
	v_mov_b32_e32 v81, v0
	v_mov_b32_e32 v82, v0
	v_mov_b32_e32 v83, v0
	v_mov_b32_e32 v84, v0
	v_mov_b32_e32 v85, v0
	v_mov_b32_e32 v86, v0
	v_mov_b32_e32 v87, v0
	v_mov_b32_e32 v96, v0
	v_mov_b32_e32 v97, v0
	v_mov_b32_e32 v98, v0
	v_mov_b32_e32 v99, v0
	v_mov_b32_e32 v100, v0
	v_mov_b32_e32 v101, v0
	v_mov_b32_e32 v102, v0
	v_mov_b32_e32 v103, v0
	v_mov_b32_e32 v112, v0
	v_mov_b32_e32 v113, v0
	v_mov_b32_e32 v114, v0
	v_mov_b32_e32 v115, v0
	v_mov_b32_e32 v116, v0
	v_mov_b32_e32 v117, v0
	v_mov_b32_e32 v118, v0
	v_mov_b32_e32 v119, v0
	v_mov_b32_e32 v120, v0
	v_mov_b32_e32 v121, v0
	v_mov_b32_e32 v122, v0
	v_mov_b32_e32 v123, v0
	v_mov_b32_e32 v124, v0
	v_mov_b32_e32 v125, v0
	v_mov_b32_e32 v126, v0
	v_mov_b32_e32 v127, v0
	.p2align	6

; template <class Units>
; DI void gemm_phase(LAS unsigned char* lds, const int wid, const int lda, const int ldb, const int K, const Units& U) {
;     ...
;     for (int ui = 0;; ++ui) {
;         const bool has_next = U.get(ui + 1, pa, pb, Enxt);
;         const char* nA = has_next ? (const char*)pa : cA; const char* nB = has_next ? (const char*)pb : cB;
;         for (int t = 0; t < nt; t += 2) {
.LBB0_1247:
	v_mov_b32_e32 v0, 0
	s_mov_b32 s15, -2
	s_mov_b32 s30, 0x60080
	v_mov_b32_e32 v1, v0
	v_mov_b32_e32 v2, v0
	v_mov_b32_e32 v3, v0
	v_mov_b32_e32 v4, v0
	v_mov_b32_e32 v5, v0
	v_mov_b32_e32 v6, v0
	v_mov_b32_e32 v7, v0
	v_mov_b32_e32 v16, v0
	v_mov_b32_e32 v17, v0
	v_mov_b32_e32 v18, v0
	v_mov_b32_e32 v19, v0
	v_mov_b32_e32 v20, v0
	v_mov_b32_e32 v21, v0
	v_mov_b32_e32 v22, v0
	v_mov_b32_e32 v23, v0
	v_mov_b32_e32 v32, v0
	v_mov_b32_e32 v33, v0
	v_mov_b32_e32 v34, v0
	v_mov_b32_e32 v35, v0
	v_mov_b32_e32 v36, v0
	v_mov_b32_e32 v37, v0
	v_mov_b32_e32 v38, v0
	v_mov_b32_e32 v39, v0
	v_mov_b32_e32 v48, v0
	v_mov_b32_e32 v49, v0
	v_mov_b32_e32 v50, v0
	v_mov_b32_e32 v51, v0
	v_mov_b32_e32 v52, v0
	v_mov_b32_e32 v53, v0
	v_mov_b32_e32 v54, v0
	v_mov_b32_e32 v55, v0
	v_mov_b32_e32 v8, v0
	v_mov_b32_e32 v9, v0
	v_mov_b32_e32 v10, v0
	v_mov_b32_e32 v11, v0
	v_mov_b32_e32 v12, v0
	v_mov_b32_e32 v13, v0
	v_mov_b32_e32 v14, v0
	v_mov_b32_e32 v15, v0
	v_mov_b32_e32 v24, v0
	v_mov_b32_e32 v25, v0
	v_mov_b32_e32 v26, v0
	v_mov_b32_e32 v27, v0
	v_mov_b32_e32 v28, v0
	v_mov_b32_e32 v29, v0
	v_mov_b32_e32 v30, v0
	v_mov_b32_e32 v31, v0
	v_mov_b32_e32 v40, v0
	v_mov_b32_e32 v41, v0
	v_mov_b32_e32 v42, v0
	v_mov_b32_e32 v43, v0
	v_mov_b32_e32 v44, v0
	v_mov_b32_e32 v45, v0
	v_mov_b32_e32 v46, v0
	v_mov_b32_e32 v47, v0
	v_mov_b32_e32 v56, v0
	v_mov_b32_e32 v57, v0
	v_mov_b32_e32 v58, v0
	v_mov_b32_e32 v59, v0
	v_mov_b32_e32 v60, v0
	v_mov_b32_e32 v61, v0
	v_mov_b32_e32 v62, v0
	v_mov_b32_e32 v63, v0
	v_mov_b32_e32 v64, v0
	v_mov_b32_e32 v65, v0
	v_mov_b32_e32 v66, v0
	v_mov_b32_e32 v67, v0
	v_mov_b32_e32 v68, v0
	v_mov_b32_e32 v69, v0
	v_mov_b32_e32 v70, v0
	v_mov_b32_e32 v71, v0
	v_mov_b32_e32 v80, v0
	v_mov_b32_e32 v81, v0
	v_mov_b32_e32 v82, v0
	v_mov_b32_e32 v83, v0
	v_mov_b32_e32 v84, v0
	v_mov_b32_e32 v85, v0
	v_mov_b32_e32 v86, v0
	v_mov_b32_e32 v87, v0
	v_mov_b32_e32 v96, v0
	v_mov_b32_e32 v97, v0
	v_mov_b32_e32 v98, v0
	v_mov_b32_e32 v99, v0
	v_mov_b32_e32 v100, v0
	v_mov_b32_e32 v101, v0
	v_mov_b32_e32 v102, v0
	v_mov_b32_e32 v103, v0
	v_mov_b32_e32 v112, v0
	v_mov_b32_e32 v113, v0
	v_mov_b32_e32 v114, v0
	v_mov_b32_e32 v115, v0
	v_mov_b32_e32 v116, v0
	v_mov_b32_e32 v117, v0
	v_mov_b32_e32 v118, v0
	v_mov_b32_e32 v119, v0
	v_mov_b32_e32 v72, v0
	v_mov_b32_e32 v73, v0
	v_mov_b32_e32 v74, v0
	v_mov_b32_e32 v75, v0
	v_mov_b32_e32 v76, v0
	v_mov_b32_e32 v77, v0
	v_mov_b32_e32 v78, v0
	v_mov_b32_e32 v79, v0
	v_mov_b32_e32 v88, v0
	v_mov_b32_e32 v89, v0
	v_mov_b32_e32 v90, v0
	v_mov_b32_e32 v91, v0
	v_mov_b32_e32 v92, v0
	v_mov_b32_e32 v93, v0
	v_mov_b32_e32 v94, v0
	v_mov_b32_e32 v95, v0
	v_mov_b32_e32 v104, v0
	v_mov_b32_e32 v105, v0
	v_mov_b32_e32 v106, v0
	v_mov_b32_e32 v107, v0
	v_mov_b32_e32 v108, v0
	v_mov_b32_e32 v109, v0
	v_mov_b32_e32 v110, v0
	v_mov_b32_e32 v111, v0
	v_mov_b32_e32 v120, v0
	v_mov_b32_e32 v121, v0
	v_mov_b32_e32 v122, v0
	v_mov_b32_e32 v123, v0
	v_mov_b32_e32 v124, v0
	v_mov_b32_e32 v125, v0
	v_mov_b32_e32 v126, v0
	v_mov_b32_e32 v127, v0
	.p2align	6
